# F1 merge GEMM: 6 of the 8 first-half epilogue gate loads issued before the K loop into free VGPRs (v228-251) so they arrive under the main loop instead of in the epilogue burst
# speedup vs baseline: 1.0035x; 1.0035x over previous
.LBB0_726:
	s_or_b64 exec, exec, s[4:5]
	s_waitcnt lgkmcnt(0)
	s_barrier
	ds_read_b32 v1, v87
	s_movk_i32 s1, 0x4ff
	s_mov_b64 s[4:5], -1
	s_waitcnt lgkmcnt(0)
	v_cmp_lt_i32_e32 vcc, s1, v1
	v_readfirstlane_b32 s0, v1
	s_cbranch_vccnz .LBB0_721
	s_cmpk_gt_i32 s0, 0xff
	s_cbranch_scc0 .LBB0_754
	v_mov_b32_e32 v1, v216
	s_add_i32 s14, s0, 0xffffff00
	s_lshr_b32 s10, s14, 2
	v_readfirstlane_b32 s1, v1
	v_and_b32_e32 v24, 15, v1
	s_bfe_u32 s4, s1, 0x20006
	s_lshl_b32 s11, s4, 4
	v_lshl_or_b32 v25, s10, 6, v24
	v_or_b32_e32 v54, s11, v25
	v_mov_b64_e32 v[2:3], s[92:93]
	s_and_b32 s15, s0, 3
	v_mad_u64_u32 v[56:57], s[6:7], v54, s80, v[2:3]
	v_bfe_u32 v1, v1, 4, 2
	s_lshl_b32 s6, s15, 8
	s_mov_b32 s7, s84
	v_mad_u64_u32 v[2:3], s[8:9], v25, s80, v[2:3]
	v_lshlrev_b32_e32 v6, 4, v1
	v_mov_b32_e32 v7, v0
	v_lshl_add_u64 v[2:3], v[2:3], 0, s[6:7]
	v_lshl_add_u64 v[12:13], v[2:3], 0, v[6:7]
	s_mov_b32 s5, 0x4b03000
	v_add_co_u32_e32 v2, vcc, s5, v12
	v_lshl_add_u64 v[4:5], v[56:57], 0, s[6:7]
	s_nop 0
	v_addc_co_u32_e32 v3, vcc, 0, v13, vcc
	v_lshl_add_u64 v[10:11], v[4:5], 0, v[6:7]
	global_load_dwordx4 v[2:5], v[2:3], off offset:2048
	v_add_co_u32_e32 v6, vcc, s5, v10
	v_lshl_add_u64 v[12:13], v[12:13], 0, s[18:19]
	s_nop 0
	v_addc_co_u32_e32 v7, vcc, 0, v11, vcc
	global_load_dwordx4 v[6:9], v[6:7], off offset:1024
	s_mov_b64 s[8:9], 0x4b03400
	global_load_dwordx4 v[26:29], v[12:13], off offset:64
	global_load_dwordx4 v[30:33], v[12:13], off offset:128
	v_lshl_add_u64 v[18:19], v[10:11], 0, s[8:9]
	global_load_dwordx4 v[14:17], v[18:19], off offset:64
	global_load_dwordx4 v[34:37], v[12:13], off offset:192
	s_nop 0
	global_load_dwordx4 v[10:13], v[18:19], off offset:192
	s_lshl_b32 s5, s15, 7
	global_load_dwordx4 v[18:21], v[18:19], off offset:128
	v_lshlrev_b32_e32 v22, 3, v1
	v_or_b32_e32 v55, s11, v24
	v_lshlrev_b32_e32 v68, 2, v1
	s_cmp_eq_u32 s4, 0
	v_lshlrev_b32_e32 v22, 1, v22
	s_waitcnt vmcnt(6)
	v_mfma_f32_16x16x32_bf16 v[2:5], v[2:5], v[6:9], 0
	s_waitcnt vmcnt(3)
	v_mfma_f32_16x16x32_bf16 v[2:5], v[26:29], v[14:17], v[2:5]
	s_waitcnt vmcnt(0)
	v_mfma_f32_16x16x32_bf16 v[2:5], v[30:33], v[18:21], v[2:5]
	v_mfma_f32_16x16x32_bf16 v[2:5], v[34:37], v[10:13], v[2:5]
	s_cbranch_scc1 .LBB0_730
	v_or_b32_e32 v23, 16, v25
	v_mov_b64_e32 v[26:27], s[92:93]
	v_mad_u64_u32 v[26:27], s[8:9], v23, s80, v[26:27]
	s_lshl_b32 s8, s5, 1
	s_mov_b32 s9, s84
	v_lshl_add_u64 v[26:27], v[26:27], 0, s[8:9]
	v_mov_b32_e32 v23, v0
	v_lshl_add_u64 v[30:31], v[26:27], 0, v[22:23]
	v_add_co_u32_e32 v26, vcc, 0x4b03000, v30
	v_lshl_add_u64 v[38:39], v[30:31], 0, s[18:19]
	s_nop 0
	v_addc_co_u32_e32 v27, vcc, 0, v31, vcc
	global_load_dwordx4 v[26:29], v[26:27], off offset:2048
	s_nop 0
	global_load_dwordx4 v[30:33], v[38:39], off offset:64
	global_load_dwordx4 v[34:37], v[38:39], off offset:192
	v_or_b32_e32 v23, 16, v68
	global_load_dwordx4 v[38:41], v[38:39], off offset:128
	v_cmp_gt_u32_e32 vcc, v23, v55
	s_waitcnt vmcnt(3)
	v_mfma_f32_16x16x32_bf16 v[26:29], v[26:29], v[6:9], 0
	s_waitcnt vmcnt(2)
	v_mfma_f32_16x16x32_bf16 v[26:29], v[30:33], v[14:17], v[26:29]
	v_mov_b32_e32 v30, s84
	v_or_b32_e32 v31, 17, v68
	v_or_b32_e32 v32, 18, v68
	s_waitcnt vmcnt(0)
	v_mfma_f32_16x16x32_bf16 v[26:29], v[38:41], v[18:21], v[26:29]
	v_or_b32_e32 v33, 19, v68
	v_mfma_f32_16x16x32_bf16 v[26:29], v[34:37], v[10:13], v[26:29]
	s_nop 7
	v_cndmask_b32_e32 v26, v26, v30, vcc
	v_cmp_le_u32_e32 vcc, v31, v55
	s_nop 1
	v_cndmask_b32_e32 v27, 0, v27, vcc
	v_cmp_le_u32_e32 vcc, v32, v55
	s_nop 1
	v_cndmask_b32_e32 v28, 0, v28, vcc
	v_cmp_le_u32_e32 vcc, v33, v55
	s_nop 1
	v_cndmask_b32_e32 v29, 0, v29, vcc
	s_branch .LBB0_731

.LBB0_735:
	s_ashr_i32 s4, s1, 1
	s_and_b32 s7, s4, 0xffffff80
	s_mov_b32 s11, s84
	v_or_b32_e32 v60, s7, v24
	s_lshl_b64 s[8:9], s[10:11], 10
	v_readlane_b32 s4, v255, 11
	s_or_b32 s8, s8, s6
	v_lshlrev_b32_e32 v24, 1, v68
	v_mov_b32_e32 v25, v0
	v_readlane_b32 s5, v255, 12
	v_ashrrev_i32_e32 v61, 31, v60
	v_mov_b32_e32 v42, s84
	v_lshl_add_u64 v[62:63], s[4:5], 0, v[24:25]
	v_lshl_add_u64 v[24:25], s[8:9], 0, v[60:61]
	v_lshlrev_b64 v[24:25], 7, v[24:25]
	v_lshl_add_u64 v[24:25], v[62:63], 0, v[24:25]
	global_load_dwordx2 v[38:39], v[24:25], off
	global_load_dwordx2 v[40:41], v[24:25], off offset:32
	v_cmp_gt_u32_e32 vcc, v68, v55
	v_cvt_pk_bf16_f32 v52, v26, v27
	v_cvt_pk_bf16_f32 v53, v28, v29
	v_cndmask_b32_e32 v37, v2, v42, vcc
	v_cmp_lt_u32_e32 vcc, v68, v55
	v_cvt_pk_bf16_f32 v46, v31, v32
	v_cvt_pk_bf16_f32 v47, v33, v34
	v_cndmask_b32_e32 v2, v37, v2, vcc
	v_or_b32_e32 v37, 2, v68
	v_cndmask_b32_e32 v3, 0, v3, vcc
	v_cmp_le_u32_e32 vcc, v37, v55
	v_or_b32_e32 v37, 3, v68
	v_cvt_pk_bf16_f32 v50, v2, v3
	v_cndmask_b32_e32 v4, 0, v4, vcc
	v_cmp_le_u32_e32 vcc, v37, v55
	v_cndmask_b32_e64 v2, 0, 1, s[12:13]
	v_cmp_ne_u32_e64 s[4:5], 1, v2
	v_cndmask_b32_e32 v5, 0, v5, vcc
	v_cvt_pk_bf16_f32 v51, v4, v5
	v_cvt_pk_bf16_f32 v48, v30, v23
	v_cvt_pk_bf16_f32 v49, v35, v36
	s_andn2_b64 vcc, exec, s[12:13]
	s_waitcnt vmcnt(0)
	v_mfma_f32_16x16x32_bf16 v[2:5], v[38:41], v[50:53], 0
	s_cbranch_vccnz .LBB0_737
	global_load_dwordx2 v[26:27], v[24:25], off offset:64
	global_load_dwordx2 v[28:29], v[24:25], off offset:96
	s_waitcnt vmcnt(0)
	v_mfma_f32_16x16x32_bf16 v[2:5], v[26:29], v[46:49], v[2:5]
.LBB0_737:
	s_lshl_b32 s11, s15, 6
	s_and_b32 s12, s14, 0xffffff00
	s_and_b32 s10, s10, 63
	s_or_b32 s11, s12, s11
	s_or_b32 s10, s11, s10
	s_mov_b32 s11, s84
	s_lshl_b64 s[10:11], s[10:11], 16
	v_readlane_b32 s12, v255, 13
	s_add_u32 s10, s12, s10
	v_readlane_b32 s12, v255, 15
	s_addc_u32 s11, s12, s11
	v_mov_b32_e32 v23, v0
	v_lshl_add_u64 v[58:59], s[10:11], 0, v[22:23]
	v_lshlrev_b64 v[22:23], 8, v[60:61]
	v_lshl_add_u64 v[34:35], v[58:59], 0, v[22:23]
	global_load_dwordx4 v[22:25], v[34:35], off
	global_load_dwordx4 v[26:29], v[34:35], off offset:64
	global_load_dwordx4 v[30:33], v[34:35], off offset:128
	s_and_b64 vcc, exec, s[4:5]
	s_waitcnt vmcnt(2)
	v_mfma_f32_16x16x32_bf16 v[2:5], v[22:25], v[6:9], v[2:5]
	v_or_b32_e32 v22, 16, v60
	v_ashrrev_i32_e32 v23, 31, v22
	v_lshl_add_u64 v[24:25], s[8:9], 0, v[22:23]
	s_waitcnt vmcnt(1)
	v_mfma_f32_16x16x32_bf16 v[2:5], v[26:29], v[14:17], v[2:5]
	global_load_dwordx4 v[26:29], v[34:35], off offset:192
	v_lshlrev_b64 v[24:25], 7, v[24:25]
	v_lshl_add_u64 v[24:25], v[62:63], 0, v[24:25]
	s_waitcnt vmcnt(1)
	v_mfma_f32_16x16x32_bf16 v[2:5], v[30:33], v[18:21], v[2:5]
	s_waitcnt vmcnt(0)
	v_mfma_f32_16x16x32_bf16 v[42:45], v[26:29], v[10:13], v[2:5]
	s_nop 5
	global_load_dwordx2 v[2:3], v[24:25], off
	global_load_dwordx2 v[4:5], v[24:25], off offset:32
	s_waitcnt vmcnt(0)
	v_mfma_f32_16x16x32_bf16 v[2:5], v[2:5], v[50:53], 0
	s_cbranch_vccnz .LBB0_739
	global_load_dwordx2 v[26:27], v[24:25], off offset:64
	global_load_dwordx2 v[28:29], v[24:25], off offset:96
	s_waitcnt vmcnt(0)
	v_mfma_f32_16x16x32_bf16 v[2:5], v[26:29], v[46:49], v[2:5]
.LBB0_739:
	v_lshlrev_b64 v[22:23], 8, v[22:23]
	v_lshl_add_u64 v[34:35], v[58:59], 0, v[22:23]
	global_load_dwordx4 v[22:25], v[34:35], off
	global_load_dwordx4 v[26:29], v[34:35], off offset:64
	global_load_dwordx4 v[30:33], v[34:35], off offset:128
	s_and_b64 vcc, exec, s[4:5]
	s_waitcnt vmcnt(2)
	v_mfma_f32_16x16x32_bf16 v[2:5], v[22:25], v[6:9], v[2:5]
	v_or_b32_e32 v22, 32, v60
	v_ashrrev_i32_e32 v23, 31, v22
	v_lshl_add_u64 v[24:25], s[8:9], 0, v[22:23]
	s_waitcnt vmcnt(1)
	v_mfma_f32_16x16x32_bf16 v[2:5], v[26:29], v[14:17], v[2:5]
	global_load_dwordx4 v[26:29], v[34:35], off offset:192
	v_lshlrev_b64 v[24:25], 7, v[24:25]
	v_lshl_add_u64 v[24:25], v[62:63], 0, v[24:25]
	s_waitcnt vmcnt(1)
	v_mfma_f32_16x16x32_bf16 v[2:5], v[30:33], v[18:21], v[2:5]
	s_waitcnt vmcnt(0)
	v_mfma_f32_16x16x32_bf16 v[38:41], v[26:29], v[10:13], v[2:5]
	s_nop 5
	global_load_dwordx2 v[2:3], v[24:25], off
	global_load_dwordx2 v[4:5], v[24:25], off offset:32
	s_waitcnt vmcnt(0)
	v_mfma_f32_16x16x32_bf16 v[2:5], v[2:5], v[50:53], 0
	s_cbranch_vccnz .LBB0_741
	global_load_dwordx2 v[26:27], v[24:25], off offset:64
	global_load_dwordx2 v[28:29], v[24:25], off offset:96
	s_waitcnt vmcnt(0)
	v_mfma_f32_16x16x32_bf16 v[2:5], v[26:29], v[46:49], v[2:5]
.LBB0_741:
	v_lshlrev_b64 v[22:23], 8, v[22:23]
	v_lshl_add_u64 v[34:35], v[58:59], 0, v[22:23]
	global_load_dwordx4 v[22:25], v[34:35], off
	global_load_dwordx4 v[26:29], v[34:35], off offset:64
	global_load_dwordx4 v[30:33], v[34:35], off offset:128
	s_and_b64 vcc, exec, s[4:5]
	s_waitcnt vmcnt(2)
	v_mfma_f32_16x16x32_bf16 v[2:5], v[22:25], v[6:9], v[2:5]
	v_or_b32_e32 v22, 48, v60
	v_ashrrev_i32_e32 v23, 31, v22
	v_lshl_add_u64 v[24:25], s[8:9], 0, v[22:23]
	s_waitcnt vmcnt(1)
	v_mfma_f32_16x16x32_bf16 v[2:5], v[26:29], v[14:17], v[2:5]
	global_load_dwordx4 v[26:29], v[34:35], off offset:192
	v_lshlrev_b64 v[24:25], 7, v[24:25]
	v_lshl_add_u64 v[24:25], v[62:63], 0, v[24:25]
	s_waitcnt vmcnt(1)
	v_mfma_f32_16x16x32_bf16 v[2:5], v[30:33], v[18:21], v[2:5]
	s_waitcnt vmcnt(0)
	v_mfma_f32_16x16x32_bf16 v[34:37], v[26:29], v[10:13], v[2:5]
	s_nop 5
	global_load_dwordx2 v[2:3], v[24:25], off
	global_load_dwordx2 v[4:5], v[24:25], off offset:32
	s_waitcnt vmcnt(0)
	v_mfma_f32_16x16x32_bf16 v[2:5], v[2:5], v[50:53], 0
	s_cbranch_vccnz .LBB0_743
	global_load_dwordx2 v[26:27], v[24:25], off offset:64
	global_load_dwordx2 v[28:29], v[24:25], off offset:96
	s_waitcnt vmcnt(0)
	v_mfma_f32_16x16x32_bf16 v[2:5], v[26:29], v[46:49], v[2:5]
.LBB0_743:
	v_lshlrev_b64 v[22:23], 8, v[22:23]
	v_lshl_add_u64 v[64:65], v[58:59], 0, v[22:23]
	global_load_dwordx4 v[22:25], v[64:65], off
	global_load_dwordx4 v[26:29], v[64:65], off offset:64
	global_load_dwordx4 v[30:33], v[64:65], off offset:128
	s_and_b64 vcc, exec, s[4:5]
	s_waitcnt vmcnt(2)
	v_mfma_f32_16x16x32_bf16 v[2:5], v[22:25], v[6:9], v[2:5]
	v_or_b32_e32 v22, 64, v60
	v_ashrrev_i32_e32 v23, 31, v22
	v_lshl_add_u64 v[24:25], s[8:9], 0, v[22:23]
	s_waitcnt vmcnt(1)
	v_mfma_f32_16x16x32_bf16 v[2:5], v[26:29], v[14:17], v[2:5]
	global_load_dwordx4 v[26:29], v[64:65], off offset:192
	v_lshlrev_b64 v[24:25], 7, v[24:25]
	v_lshl_add_u64 v[24:25], v[62:63], 0, v[24:25]
	s_waitcnt vmcnt(1)
	v_mfma_f32_16x16x32_bf16 v[2:5], v[30:33], v[18:21], v[2:5]
	s_waitcnt vmcnt(0)
	v_mfma_f32_16x16x32_bf16 v[30:33], v[26:29], v[10:13], v[2:5]
	s_nop 5
	global_load_dwordx2 v[2:3], v[24:25], off
	global_load_dwordx2 v[4:5], v[24:25], off offset:32
	s_waitcnt vmcnt(0)
	v_mfma_f32_16x16x32_bf16 v[2:5], v[2:5], v[50:53], 0
	s_cbranch_vccnz .LBB0_745
	global_load_dwordx2 v[26:27], v[24:25], off offset:64
	global_load_dwordx2 v[28:29], v[24:25], off offset:96
	s_waitcnt vmcnt(0)
	v_mfma_f32_16x16x32_bf16 v[2:5], v[26:29], v[46:49], v[2:5]
.LBB0_745:
	v_lshlrev_b64 v[22:23], 8, v[22:23]
	v_lshl_add_u64 v[70:71], v[58:59], 0, v[22:23]
	global_load_dwordx4 v[22:25], v[70:71], off
	global_load_dwordx4 v[26:29], v[70:71], off offset:64
	global_load_dwordx4 v[64:67], v[70:71], off offset:128
	s_and_b64 vcc, exec, s[4:5]
	s_waitcnt vmcnt(2)
	v_mfma_f32_16x16x32_bf16 v[2:5], v[22:25], v[6:9], v[2:5]
	v_or_b32_e32 v22, 0x50, v60
	v_ashrrev_i32_e32 v23, 31, v22
	v_lshl_add_u64 v[24:25], s[8:9], 0, v[22:23]
	s_waitcnt vmcnt(1)
	v_mfma_f32_16x16x32_bf16 v[2:5], v[26:29], v[14:17], v[2:5]
	global_load_dwordx4 v[26:29], v[70:71], off offset:192
	v_lshlrev_b64 v[24:25], 7, v[24:25]
	v_lshl_add_u64 v[24:25], v[62:63], 0, v[24:25]
	s_waitcnt vmcnt(1)
	v_mfma_f32_16x16x32_bf16 v[2:5], v[64:67], v[18:21], v[2:5]
	s_waitcnt vmcnt(0)
	v_mfma_f32_16x16x32_bf16 v[26:29], v[26:29], v[10:13], v[2:5]
	s_nop 5
	global_load_dwordx2 v[2:3], v[24:25], off
	global_load_dwordx2 v[4:5], v[24:25], off offset:32
	s_waitcnt vmcnt(0)
	v_mfma_f32_16x16x32_bf16 v[2:5], v[2:5], v[50:53], 0
	s_cbranch_vccnz .LBB0_747
	global_load_dwordx2 v[64:65], v[24:25], off offset:64
	global_load_dwordx2 v[66:67], v[24:25], off offset:96
	s_waitcnt vmcnt(0)
	v_mfma_f32_16x16x32_bf16 v[2:5], v[64:67], v[46:49], v[2:5]
.LBB0_747:
	v_lshlrev_b64 v[22:23], 8, v[22:23]
	v_lshl_add_u64 v[70:71], v[58:59], 0, v[22:23]
	global_load_dwordx4 v[22:25], v[70:71], off
	global_load_dwordx4 v[64:67], v[70:71], off offset:64
	s_and_b64 vcc, exec, s[4:5]
	s_waitcnt vmcnt(1)
	v_mfma_f32_16x16x32_bf16 v[2:5], v[22:25], v[6:9], v[2:5]
	global_load_dwordx4 v[22:25], v[70:71], off offset:128
	s_nop 0
	global_load_dwordx4 v[70:73], v[70:71], off offset:192
	s_waitcnt vmcnt(2)
	v_mfma_f32_16x16x32_bf16 v[2:5], v[64:67], v[14:17], v[2:5]
	v_or_b32_e32 v64, 0x60, v60
	v_ashrrev_i32_e32 v65, 31, v64
	s_waitcnt vmcnt(1)
	v_mfma_f32_16x16x32_bf16 v[2:5], v[22:25], v[18:21], v[2:5]
	v_lshl_add_u64 v[22:23], s[8:9], 0, v[64:65]
	v_lshlrev_b64 v[22:23], 7, v[22:23]
	v_lshl_add_u64 v[66:67], v[62:63], 0, v[22:23]
	s_waitcnt vmcnt(0)
	v_mfma_f32_16x16x32_bf16 v[22:25], v[70:73], v[10:13], v[2:5]
	s_nop 2
	global_load_dwordx2 v[2:3], v[66:67], off
	global_load_dwordx2 v[4:5], v[66:67], off offset:32
	s_waitcnt vmcnt(0)
	v_mfma_f32_16x16x32_bf16 v[2:5], v[2:5], v[50:53], 0
	s_cbranch_vccnz .LBB0_749
	global_load_dwordx2 v[70:71], v[66:67], off offset:64
	global_load_dwordx2 v[72:73], v[66:67], off offset:96
	s_waitcnt vmcnt(0)
	v_mfma_f32_16x16x32_bf16 v[2:5], v[70:73], v[46:49], v[2:5]
.LBB0_749:
	v_lshlrev_b64 v[64:65], 8, v[64:65]
	v_lshl_add_u64 v[74:75], v[58:59], 0, v[64:65]
	global_load_dwordx4 v[64:67], v[74:75], off
	global_load_dwordx4 v[70:73], v[74:75], off offset:64
	v_or_b32_e32 v60, 0x70, v60
	v_ashrrev_i32_e32 v61, 31, v60
	s_and_b64 vcc, exec, s[4:5]
	s_waitcnt vmcnt(1)
	v_mfma_f32_16x16x32_bf16 v[2:5], v[64:67], v[6:9], v[2:5]
	global_load_dwordx4 v[64:67], v[74:75], off offset:128
	s_waitcnt vmcnt(1)
	v_mfma_f32_16x16x32_bf16 v[2:5], v[70:73], v[14:17], v[2:5]
	global_load_dwordx4 v[70:73], v[74:75], off offset:192
	s_waitcnt vmcnt(1)
	v_mfma_f32_16x16x32_bf16 v[2:5], v[64:67], v[18:21], v[2:5]
	v_lshl_add_u64 v[64:65], s[8:9], 0, v[60:61]
	v_lshlrev_b64 v[64:65], 7, v[64:65]
	v_lshl_add_u64 v[62:63], v[62:63], 0, v[64:65]
	global_load_dwordx2 v[64:65], v[62:63], off
	global_load_dwordx2 v[66:67], v[62:63], off offset:32
	s_waitcnt vmcnt(2)
	v_mfma_f32_16x16x32_bf16 v[2:5], v[70:73], v[10:13], v[2:5]
	s_waitcnt vmcnt(0)
	v_mfma_f32_16x16x32_bf16 v[50:53], v[64:67], v[50:53], 0
	s_cbranch_vccnz .LBB0_751
	global_load_dwordx2 v[64:65], v[62:63], off offset:64
	global_load_dwordx2 v[66:67], v[62:63], off offset:96
	s_waitcnt vmcnt(0)
	v_mfma_f32_16x16x32_bf16 v[50:53], v[64:67], v[46:49], v[50:53]
.LBB0_751:
	v_lshlrev_b64 v[46:47], 8, v[60:61]
	v_lshl_add_u64 v[66:67], v[58:59], 0, v[46:47]
	global_load_dwordx4 v[46:49], v[66:67], off
	global_load_dwordx4 v[58:61], v[66:67], off offset:64
	global_load_dwordx4 v[62:65], v[66:67], off offset:128
	global_load_dwordx4 v[70:73], v[66:67], off offset:192
	v_mul_f32_e32 v66, v43, v43
	v_mul_f32_e32 v67, v39, v39
	v_mul_f32_e32 v69, v35, v35
	v_fmac_f32_e32 v66, v42, v42
	v_fmac_f32_e32 v67, v38, v38
	v_mul_f32_e32 v74, v31, v31
	v_fmac_f32_e32 v69, v34, v34
	v_fmac_f32_e32 v66, v44, v44
	v_fmac_f32_e32 v67, v40, v40
	v_mul_f32_e32 v75, v27, v27
	v_fmac_f32_e32 v74, v30, v30
	v_fmac_f32_e32 v69, v36, v36
	v_fmac_f32_e32 v66, v45, v45
	v_fmac_f32_e32 v67, v41, v41
	v_mul_f32_e32 v76, v23, v23
	v_fmac_f32_e32 v75, v26, v26
	v_fmac_f32_e32 v74, v32, v32
	v_fmac_f32_e32 v69, v37, v37
	v_mul_f32_e32 v77, v3, v3
	v_fmac_f32_e32 v76, v22, v22
	v_fmac_f32_e32 v75, v28, v28
	v_fmac_f32_e32 v74, v33, v33
	v_and_b32_e32 v79, 64, v121
	v_fmac_f32_e32 v77, v2, v2
	v_fmac_f32_e32 v76, v24, v24
	v_fmac_f32_e32 v75, v29, v29
	v_xor_b32_e32 v78, 16, v121
	v_add_u32_e32 v79, 64, v79
	v_fmac_f32_e32 v77, v4, v4
	v_fmac_f32_e32 v76, v25, v25
	v_cmp_lt_i32_e32 vcc, v78, v79
	v_fmac_f32_e32 v77, v5, v5
	s_waitcnt vmcnt(3)
	v_mfma_f32_16x16x32_bf16 v[6:9], v[46:49], v[6:9], v[50:53]
	v_cndmask_b32_e32 v78, v121, v78, vcc
	s_waitcnt vmcnt(2)
	v_mfma_f32_16x16x32_bf16 v[6:9], v[58:61], v[14:17], v[6:9]
	v_add_f32_e32 v15, v66, v67
	v_add_f32_e32 v15, v15, v69
	v_add_f32_e32 v15, v15, v74
	s_waitcnt vmcnt(1)
	v_mfma_f32_16x16x32_bf16 v[6:9], v[62:65], v[18:21], v[6:9]
	v_add_f32_e32 v15, v15, v75
	v_lshlrev_b32_e32 v14, 2, v78
	s_waitcnt vmcnt(0)
	v_mfma_f32_16x16x32_bf16 v[6:9], v[70:73], v[10:13], v[6:9]
	v_add_f32_e32 v10, v15, v76
	v_add_f32_e32 v10, v10, v77
	v_xor_b32_e32 v12, 32, v121
	v_cmp_lt_i32_e32 vcc, v12, v79
	s_nop 1
	v_cndmask_b32_e32 v12, v121, v12, vcc
	s_nop 0
	v_mul_f32_e32 v11, v7, v7
	v_fmac_f32_e32 v11, v6, v6
	v_fmac_f32_e32 v11, v8, v8
	v_fmac_f32_e32 v11, v9, v9
	v_add_f32_e32 v10, v10, v11
	ds_bpermute_b32 v11, v14, v10
	v_cmp_eq_u32_e32 vcc, 0, v1
	s_waitcnt lgkmcnt(0)
	v_add_f32_e32 v10, v10, v11
	v_lshlrev_b32_e32 v11, 2, v12
	ds_bpermute_b32 v11, v11, v10
	s_and_saveexec_b64 s[4:5], vcc
	s_cbranch_execz .LBB0_753
	s_and_b32 s1, s1, 0xffffff00
	s_add_i32 s1, s1, 0
	s_waitcnt lgkmcnt(0)
	v_add_f32_e32 v1, v10, v11
	v_lshl_add_u32 v10, v55, 2, s1
	v_add_u32_e32 v10, 0x20040, v10
	ds_write_b32 v10, v1

.LBB0_876:
	s_lshl_b32 s98, s7, 12
	s_add_u32 s98, s39, s98
	s_addc_u32 s99, s40, 0
	s_lshl_b32 s100, s6, 8
	v_add_u32_e32 v252, s100, v217
	v_lshl_or_b32 v254, s49, 8, v222
	v_lshlrev_b32_e32 v252, 14, v252
	v_lshl_add_u32 v252, v254, 1, v252
	global_load_dwordx4 v[228:231], v252, s[98:99]
	global_load_dwordx4 v[232:235], v252, s[98:99] offset:256
	v_add_u32_e32 v253, 0x40000, v252
	global_load_dwordx4 v[236:239], v253, s[98:99]
	global_load_dwordx4 v[240:243], v253, s[98:99] offset:256
	v_add_u32_e32 v254, 0x80000, v252
	global_load_dwordx4 v[244:247], v254, s[98:99]
	global_load_dwordx4 v[248:251], v254, s[98:99] offset:256
	s_add_u32 s17, s24, 0x100
	s_addc_u32 s50, s25, 0
	s_add_u32 s22, s22, 0x40080
	v_mov_b32_e32 v0, 0
	s_addc_u32 s23, s23, 0
	s_mov_b32 s51, -2
	v_mov_b32_e32 v1, v0
	v_mov_b32_e32 v2, v0
	v_mov_b32_e32 v3, v0
	v_mov_b32_e32 v4, v0
	v_mov_b32_e32 v5, v0
	v_mov_b32_e32 v6, v0
	v_mov_b32_e32 v7, v0
	v_mov_b32_e32 v16, v0
	v_mov_b32_e32 v17, v0
	v_mov_b32_e32 v18, v0
	v_mov_b32_e32 v19, v0
	v_mov_b32_e32 v20, v0
	v_mov_b32_e32 v21, v0
	v_mov_b32_e32 v22, v0
	v_mov_b32_e32 v23, v0
	v_mov_b32_e32 v32, v0
	v_mov_b32_e32 v33, v0
	v_mov_b32_e32 v34, v0
	v_mov_b32_e32 v35, v0
	v_mov_b32_e32 v36, v0
	v_mov_b32_e32 v37, v0
	v_mov_b32_e32 v38, v0
	v_mov_b32_e32 v39, v0
	v_mov_b32_e32 v48, v0
	v_mov_b32_e32 v49, v0
	v_mov_b32_e32 v50, v0
	v_mov_b32_e32 v51, v0
	v_mov_b32_e32 v52, v0
	v_mov_b32_e32 v53, v0
	v_mov_b32_e32 v54, v0
	v_mov_b32_e32 v55, v0
	v_mov_b32_e32 v8, v0
	v_mov_b32_e32 v9, v0
	v_mov_b32_e32 v10, v0
	v_mov_b32_e32 v11, v0
	v_mov_b32_e32 v12, v0
	v_mov_b32_e32 v13, v0
	v_mov_b32_e32 v14, v0
	v_mov_b32_e32 v15, v0
	v_mov_b32_e32 v24, v0
	v_mov_b32_e32 v25, v0
	v_mov_b32_e32 v26, v0
	v_mov_b32_e32 v27, v0
	v_mov_b32_e32 v28, v0
	v_mov_b32_e32 v29, v0
	v_mov_b32_e32 v30, v0
	v_mov_b32_e32 v31, v0
	v_mov_b32_e32 v40, v0
	v_mov_b32_e32 v41, v0
	v_mov_b32_e32 v42, v0
	v_mov_b32_e32 v43, v0
	v_mov_b32_e32 v44, v0
	v_mov_b32_e32 v45, v0
	v_mov_b32_e32 v46, v0
	v_mov_b32_e32 v47, v0
	v_mov_b32_e32 v56, v0
	v_mov_b32_e32 v57, v0
	v_mov_b32_e32 v58, v0
	v_mov_b32_e32 v59, v0
	v_mov_b32_e32 v60, v0
	v_mov_b32_e32 v61, v0
	v_mov_b32_e32 v62, v0
	v_mov_b32_e32 v63, v0
	v_mov_b32_e32 v72, v0
	v_mov_b32_e32 v73, v0
	v_mov_b32_e32 v74, v0
	v_mov_b32_e32 v75, v0
	v_mov_b32_e32 v76, v0
	v_mov_b32_e32 v77, v0
	v_mov_b32_e32 v78, v0
	v_mov_b32_e32 v79, v0
	v_mov_b32_e32 v96, v0
	v_mov_b32_e32 v97, v0
	v_mov_b32_e32 v98, v0
	v_mov_b32_e32 v99, v0
	v_mov_b32_e32 v104, v0
	v_mov_b32_e32 v105, v0
	v_mov_b32_e32 v106, v0
	v_mov_b32_e32 v107, v0
	v_mov_b32_e32 v124, v0
	v_mov_b32_e32 v125, v0
	v_mov_b32_e32 v126, v0
	v_mov_b32_e32 v127, v0
	v_mov_b32_e32 v128, v0
	v_mov_b32_e32 v129, v0
	v_mov_b32_e32 v130, v0
	v_mov_b32_e32 v131, v0
	v_mov_b32_e32 v144, v0
	v_mov_b32_e32 v145, v0
	v_mov_b32_e32 v146, v0
	v_mov_b32_e32 v147, v0
	v_mov_b32_e32 v148, v0
	v_mov_b32_e32 v149, v0
	v_mov_b32_e32 v150, v0
	v_mov_b32_e32 v151, v0
	v_mov_b32_e32 v84, v0
	v_mov_b32_e32 v85, v0
	v_mov_b32_e32 v86, v0
	v_mov_b32_e32 v87, v0
	v_mov_b32_e32 v92, v0
	v_mov_b32_e32 v93, v0
	v_mov_b32_e32 v94, v0
	v_mov_b32_e32 v95, v0
	v_mov_b32_e32 v112, v0
	v_mov_b32_e32 v113, v0
	v_mov_b32_e32 v114, v0
	v_mov_b32_e32 v115, v0
	v_mov_b32_e32 v116, v0
	v_mov_b32_e32 v117, v0
	v_mov_b32_e32 v118, v0
	v_mov_b32_e32 v119, v0
	v_mov_b32_e32 v136, v0
	v_mov_b32_e32 v137, v0
	v_mov_b32_e32 v138, v0
	v_mov_b32_e32 v139, v0
	v_mov_b32_e32 v140, v0
	v_mov_b32_e32 v141, v0
	v_mov_b32_e32 v142, v0
	v_mov_b32_e32 v143, v0
	v_mov_b32_e32 v152, v0
	v_mov_b32_e32 v153, v0
	v_mov_b32_e32 v154, v0
	v_mov_b32_e32 v155, v0
	v_mov_b32_e32 v156, v0
	v_mov_b32_e32 v157, v0
	v_mov_b32_e32 v158, v0
	v_mov_b32_e32 v159, v0

.LBB0_880:
	s_lshl_b32 s22, s7, 11
	s_ashr_i32 s23, s22, 31
	s_cmp_lg_u32 s7, 0
	s_cselect_b64 s[24:25], -1, 0
	s_lshl_b32 s17, s6, 8
	s_lshl_b64 s[22:23], s[22:23], 1
	v_add_u32_e32 v210, s17, v217
	s_add_u32 s22, s39, s22
	v_ashrrev_i32_e32 v211, 31, v210
	s_addc_u32 s23, s40, s23
	v_lshl_or_b32 v208, s49, 8, v222
	v_lshlrev_b64 v[64:65], 14, v[210:211]
	v_lshl_add_u64 v[64:65], s[22:23], 0, v[64:65]
	v_ashrrev_i32_e32 v209, 31, v208
	v_lshl_add_u64 v[64:65], v[208:209], 1, v[64:65]
	v_lshlrev_b64 v[66:67], 12, v[210:211]
	v_lshl_add_u64 v[66:67], s[10:11], 0, v[66:67]
	s_cmp_eq_u32 s7, 0
	v_lshl_add_u64 v[212:213], v[208:209], 1, v[66:67]
	s_cbranch_scc1 .LBB0_882
	global_load_dwordx4 v[132:135], v[212:213], off
.LBB0_882:
	v_cndmask_b32_e64 v64, 0, 1, s[24:25]
	v_cmp_ne_u32_e64 s[6:7], 1, v64
	s_andn2_b64 vcc, exec, s[24:25]
	s_cbranch_vccnz .LBB0_884
	global_load_dwordx4 v[120:123], v[212:213], off offset:256
.LBB0_884:
	v_or_b32_e32 v64, 16, v210
	v_ashrrev_i32_e32 v65, 31, v64
	v_lshlrev_b64 v[66:67], 14, v[64:65]
	v_lshl_add_u64 v[66:67], s[22:23], 0, v[66:67]
	v_lshl_add_u64 v[66:67], v[208:209], 1, v[66:67]
	v_lshlrev_b64 v[64:65], 12, v[64:65]
	v_lshl_add_u64 v[64:65], s[10:11], 0, v[64:65]
	s_and_b64 vcc, exec, s[6:7]
	v_lshl_add_u64 v[64:65], v[208:209], 1, v[64:65]
	s_cbranch_vccnz .LBB0_886
	global_load_dwordx4 v[108:111], v[64:65], off
.LBB0_886:
	s_and_b64 vcc, exec, s[6:7]
	s_cbranch_vccnz .LBB0_888
	global_load_dwordx4 v[100:103], v[64:65], off offset:256
.LBB0_888:
	v_or_b32_e32 v64, 32, v210
	v_ashrrev_i32_e32 v65, 31, v64
	v_lshlrev_b64 v[66:67], 14, v[64:65]
	v_lshl_add_u64 v[66:67], s[22:23], 0, v[66:67]
	v_lshl_add_u64 v[66:67], v[208:209], 1, v[66:67]
	v_lshlrev_b64 v[64:65], 12, v[64:65]
	v_lshl_add_u64 v[64:65], s[10:11], 0, v[64:65]
	s_and_b64 vcc, exec, s[6:7]
	v_lshl_add_u64 v[64:65], v[208:209], 1, v[64:65]
	s_cbranch_vccnz .LBB0_890
	global_load_dwordx4 v[88:91], v[64:65], off
.LBB0_890:
	s_and_b64 vcc, exec, s[6:7]
	s_cbranch_vccnz .LBB0_892
	global_load_dwordx4 v[80:83], v[64:65], off offset:256

.LBB0_896:
	s_waitcnt vmcnt(0)
	v_lshlrev_b32_e32 v214, 16, v228
	v_and_b32_e32 v215, 0xffff0000, v228
	v_lshlrev_b32_e32 v228, 16, v229
	v_and_b32_e32 v229, 0xffff0000, v229
	v_pk_mul_f32 v[158:159], v[158:159], v[228:229]
	v_lshlrev_b32_e32 v228, 16, v230
	v_and_b32_e32 v229, 0xffff0000, v230
	v_pk_mul_f32 v[152:153], v[152:153], v[228:229]
	v_lshlrev_b32_e32 v228, 16, v231
	v_and_b32_e32 v229, 0xffff0000, v231
	v_pk_mul_f32 v[156:157], v[156:157], v[214:215]
	s_and_b64 vcc, exec, s[6:7]
	v_pk_mul_f32 v[154:155], v[154:155], v[228:229]
	s_cbranch_vccnz .LBB0_898
	v_lshlrev_b32_e32 v228, 16, v132
	v_and_b32_e32 v229, 0xffff0000, v132
	v_lshlrev_b32_e32 v230, 16, v133
	v_and_b32_e32 v231, 0xffff0000, v133
	v_lshlrev_b32_e32 v214, 16, v134
	v_and_b32_e32 v215, 0xffff0000, v134
	v_lshlrev_b32_e32 v226, 16, v135
	v_and_b32_e32 v227, 0xffff0000, v135
	v_pk_add_f32 v[158:159], v[158:159], v[230:231]
	v_pk_add_f32 v[156:157], v[156:157], v[228:229]
	v_pk_add_f32 v[154:155], v[154:155], v[226:227]
	v_pk_add_f32 v[152:153], v[152:153], v[214:215]
.LBB0_898:
	v_cvt_pk_bf16_f32 v156, v156, v157
	v_cvt_pk_bf16_f32 v157, v158, v159
	v_cvt_pk_bf16_f32 v158, v152, v153
	v_lshlrev_b32_e32 v152, 16, v232
	v_and_b32_e32 v153, 0xffff0000, v232
	v_pk_mul_f32 v[148:149], v[148:149], v[152:153]
	v_lshlrev_b32_e32 v152, 16, v233
	v_and_b32_e32 v153, 0xffff0000, v233
	v_pk_mul_f32 v[150:151], v[150:151], v[152:153]
	v_lshlrev_b32_e32 v152, 16, v234
	v_and_b32_e32 v153, 0xffff0000, v234
	v_pk_mul_f32 v[144:145], v[144:145], v[152:153]
	v_lshlrev_b32_e32 v152, 16, v235
	v_and_b32_e32 v153, 0xffff0000, v235
	v_cvt_pk_bf16_f32 v159, v154, v155
	s_and_b64 vcc, exec, s[6:7]
	v_pk_mul_f32 v[146:147], v[146:147], v[152:153]
	global_store_dwordx4 v[212:213], v[156:159], off
	s_cbranch_vccnz .LBB0_900
	v_lshlrev_b32_e32 v152, 16, v120
	v_and_b32_e32 v153, 0xffff0000, v120
	v_lshlrev_b32_e32 v154, 16, v121
	v_and_b32_e32 v155, 0xffff0000, v121
	v_lshlrev_b32_e32 v156, 16, v122
	v_and_b32_e32 v157, 0xffff0000, v122
	v_lshlrev_b32_e32 v158, 16, v123
	v_and_b32_e32 v159, 0xffff0000, v123
	v_pk_add_f32 v[150:151], v[150:151], v[154:155]
	v_pk_add_f32 v[148:149], v[148:149], v[152:153]
	v_pk_add_f32 v[146:147], v[146:147], v[158:159]
	v_pk_add_f32 v[144:145], v[144:145], v[156:157]
.LBB0_900:
	v_cvt_pk_bf16_f32 v148, v148, v149
	v_cvt_pk_bf16_f32 v149, v150, v151
	v_cvt_pk_bf16_f32 v150, v144, v145
	v_lshlrev_b32_e32 v144, 16, v236
	v_and_b32_e32 v145, 0xffff0000, v236
	v_pk_mul_f32 v[140:141], v[140:141], v[144:145]
	v_lshlrev_b32_e32 v144, 16, v237
	v_and_b32_e32 v145, 0xffff0000, v237
	v_pk_mul_f32 v[142:143], v[142:143], v[144:145]
	v_lshlrev_b32_e32 v144, 16, v238
	v_and_b32_e32 v145, 0xffff0000, v238
	v_pk_mul_f32 v[136:137], v[136:137], v[144:145]
	v_lshlrev_b32_e32 v144, 16, v239
	v_and_b32_e32 v145, 0xffff0000, v239
	v_cvt_pk_bf16_f32 v151, v146, v147
	s_and_b64 vcc, exec, s[6:7]
	v_pk_mul_f32 v[138:139], v[138:139], v[144:145]
	global_store_dwordx4 v[212:213], v[148:151], off offset:256
	s_cbranch_vccnz .LBB0_902
	v_lshlrev_b32_e32 v144, 16, v108
	v_and_b32_e32 v145, 0xffff0000, v108
	v_lshlrev_b32_e32 v146, 16, v109
	v_and_b32_e32 v147, 0xffff0000, v109
	v_lshlrev_b32_e32 v148, 16, v110
	v_and_b32_e32 v149, 0xffff0000, v110
	v_lshlrev_b32_e32 v150, 16, v111
	v_and_b32_e32 v151, 0xffff0000, v111
	v_pk_add_f32 v[142:143], v[142:143], v[146:147]
	v_pk_add_f32 v[140:141], v[140:141], v[144:145]
	v_pk_add_f32 v[138:139], v[138:139], v[150:151]
	v_pk_add_f32 v[136:137], v[136:137], v[148:149]
.LBB0_902:
	v_add_u32_e32 v144, s17, v219
	v_cvt_pk_bf16_f32 v140, v140, v141
	v_cvt_pk_bf16_f32 v141, v142, v143
	v_cvt_pk_bf16_f32 v143, v138, v139
	v_lshlrev_b32_e32 v138, 16, v240
	v_and_b32_e32 v139, 0xffff0000, v240
	v_ashrrev_i32_e32 v145, 31, v144
	v_pk_mul_f32 v[128:129], v[128:129], v[138:139]
	v_lshlrev_b32_e32 v138, 16, v241
	v_and_b32_e32 v139, 0xffff0000, v241
	v_cvt_pk_bf16_f32 v142, v136, v137
	v_lshlrev_b64 v[136:137], 12, v[144:145]
	v_pk_mul_f32 v[130:131], v[130:131], v[138:139]
	v_lshlrev_b32_e32 v138, 16, v242
	v_and_b32_e32 v139, 0xffff0000, v242
	v_lshl_add_u64 v[136:137], s[10:11], 0, v[136:137]
	v_pk_mul_f32 v[124:125], v[124:125], v[138:139]
	v_lshlrev_b32_e32 v138, 16, v243
	v_and_b32_e32 v139, 0xffff0000, v243
	v_lshl_add_u64 v[136:137], v[208:209], 1, v[136:137]
	s_and_b64 vcc, exec, s[6:7]
	v_pk_mul_f32 v[126:127], v[126:127], v[138:139]
	global_store_dwordx4 v[136:137], v[140:143], off
	s_cbranch_vccnz .LBB0_904
	v_lshlrev_b32_e32 v138, 16, v100
	v_and_b32_e32 v139, 0xffff0000, v100
	v_lshlrev_b32_e32 v140, 16, v101
	v_and_b32_e32 v141, 0xffff0000, v101
	v_lshlrev_b32_e32 v142, 16, v102
	v_and_b32_e32 v143, 0xffff0000, v102
	v_lshlrev_b32_e32 v144, 16, v103
	v_and_b32_e32 v145, 0xffff0000, v103
	v_pk_add_f32 v[130:131], v[130:131], v[140:141]
	v_pk_add_f32 v[128:129], v[128:129], v[138:139]
	v_pk_add_f32 v[126:127], v[126:127], v[144:145]
	v_pk_add_f32 v[124:125], v[124:125], v[142:143]
.LBB0_904:
	v_cvt_pk_bf16_f32 v128, v128, v129
	v_cvt_pk_bf16_f32 v129, v130, v131
	v_cvt_pk_bf16_f32 v130, v124, v125
	v_lshlrev_b32_e32 v124, 16, v244
	v_and_b32_e32 v125, 0xffff0000, v244
	v_pk_mul_f32 v[116:117], v[116:117], v[124:125]
	v_lshlrev_b32_e32 v124, 16, v245
	v_and_b32_e32 v125, 0xffff0000, v245
	v_pk_mul_f32 v[118:119], v[118:119], v[124:125]
	v_lshlrev_b32_e32 v124, 16, v246
	v_and_b32_e32 v125, 0xffff0000, v246
	v_pk_mul_f32 v[112:113], v[112:113], v[124:125]
	v_lshlrev_b32_e32 v124, 16, v247
	v_and_b32_e32 v125, 0xffff0000, v247
	v_cvt_pk_bf16_f32 v131, v126, v127
	s_and_b64 vcc, exec, s[6:7]
	v_pk_mul_f32 v[114:115], v[114:115], v[124:125]
	global_store_dwordx4 v[136:137], v[128:131], off offset:256
	s_cbranch_vccnz .LBB0_906
	v_lshlrev_b32_e32 v124, 16, v88
	v_and_b32_e32 v125, 0xffff0000, v88
	v_lshlrev_b32_e32 v126, 16, v89
	v_and_b32_e32 v127, 0xffff0000, v89
	v_lshlrev_b32_e32 v128, 16, v90
	v_and_b32_e32 v129, 0xffff0000, v90
	v_lshlrev_b32_e32 v130, 16, v91
	v_and_b32_e32 v131, 0xffff0000, v91
	v_pk_add_f32 v[118:119], v[118:119], v[126:127]
	v_pk_add_f32 v[116:117], v[116:117], v[124:125]
	v_pk_add_f32 v[114:115], v[114:115], v[130:131]
	v_pk_add_f32 v[112:113], v[112:113], v[128:129]
.LBB0_906:
	v_add_u32_e32 v124, s17, v220
	v_cvt_pk_bf16_f32 v116, v116, v117
	v_cvt_pk_bf16_f32 v117, v118, v119
	v_cvt_pk_bf16_f32 v119, v114, v115
	v_lshlrev_b32_e32 v114, 16, v248
	v_and_b32_e32 v115, 0xffff0000, v248
	v_ashrrev_i32_e32 v125, 31, v124
	v_pk_mul_f32 v[104:105], v[104:105], v[114:115]
	v_lshlrev_b32_e32 v114, 16, v249
	v_and_b32_e32 v115, 0xffff0000, v249
	v_cvt_pk_bf16_f32 v118, v112, v113
	v_lshlrev_b64 v[112:113], 12, v[124:125]
	v_pk_mul_f32 v[106:107], v[106:107], v[114:115]
	v_lshlrev_b32_e32 v114, 16, v250
	v_and_b32_e32 v115, 0xffff0000, v250
	v_lshl_add_u64 v[112:113], s[10:11], 0, v[112:113]
	v_pk_mul_f32 v[96:97], v[96:97], v[114:115]
	v_lshlrev_b32_e32 v114, 16, v251
	v_and_b32_e32 v115, 0xffff0000, v251
	v_lshl_add_u64 v[112:113], v[208:209], 1, v[112:113]
	s_and_b64 vcc, exec, s[6:7]
	v_pk_mul_f32 v[98:99], v[98:99], v[114:115]
	global_store_dwordx4 v[112:113], v[116:119], off
	s_cbranch_vccnz .LBB0_908
	v_lshlrev_b32_e32 v114, 16, v80
	v_and_b32_e32 v115, 0xffff0000, v80
	v_lshlrev_b32_e32 v116, 16, v81
	v_and_b32_e32 v117, 0xffff0000, v81
	v_lshlrev_b32_e32 v118, 16, v82
	v_and_b32_e32 v119, 0xffff0000, v82
	v_lshlrev_b32_e32 v124, 16, v83
	v_and_b32_e32 v125, 0xffff0000, v83
	v_pk_add_f32 v[106:107], v[106:107], v[116:117]
	v_pk_add_f32 v[104:105], v[104:105], v[114:115]
	v_pk_add_f32 v[98:99], v[98:99], v[124:125]
	v_pk_add_f32 v[96:97], v[96:97], v[118:119]

.LBB0_1781:
	s_or_b64 exec, exec, s[2:3]
	s_waitcnt lgkmcnt(0)
	s_barrier
	ds_read_b32 v1, v87
	s_movk_i32 s1, 0x4ff
	s_mov_b64 s[2:3], -1
	s_waitcnt lgkmcnt(0)
	v_cmp_lt_i32_e32 vcc, s1, v1
	v_readfirstlane_b32 s0, v1
	s_cbranch_vccnz .LBB0_1776
	s_cmpk_gt_i32 s0, 0xff
	s_cbranch_scc0 .LBB0_1809
	v_mov_b32_e32 v1, v216
	s_add_i32 s12, s0, 0xffffff00
	s_lshr_b32 s8, s12, 2
	v_readfirstlane_b32 s1, v1
	v_and_b32_e32 v24, 15, v1
	s_bfe_u32 s4, s1, 0x20006
	s_lshl_b32 s5, s4, 4
	v_lshl_or_b32 v25, s8, 6, v24
	v_or_b32_e32 v54, s5, v25
	v_mov_b64_e32 v[2:3], s[92:93]
	s_and_b32 s13, s0, 3
	v_mad_u64_u32 v[56:57], s[2:3], v54, s17, v[2:3]
	v_bfe_u32 v1, v1, 4, 2
	s_lshl_b32 s2, s13, 8
	s_mov_b32 s3, s84
	v_mad_u64_u32 v[2:3], s[6:7], v25, s17, v[2:3]
	v_lshlrev_b32_e32 v6, 4, v1
	v_mov_b32_e32 v7, v0
	v_lshl_add_u64 v[2:3], v[2:3], 0, s[2:3]
	v_lshl_add_u64 v[4:5], v[56:57], 0, s[2:3]
	v_lshl_add_u64 v[12:13], v[2:3], 0, v[6:7]
	s_mov_b32 s3, 0x4b03000
	v_add_co_u32_e32 v2, vcc, s3, v12
	v_lshl_add_u64 v[10:11], v[4:5], 0, v[6:7]
	s_nop 0
	v_addc_co_u32_e32 v3, vcc, 0, v13, vcc
	global_load_dwordx4 v[2:5], v[2:3], off offset:2048
	v_add_co_u32_e32 v6, vcc, s3, v10
	v_lshl_add_u64 v[12:13], v[12:13], 0, s[18:19]
	s_nop 0
	v_addc_co_u32_e32 v7, vcc, 0, v11, vcc
	global_load_dwordx4 v[6:9], v[6:7], off offset:1024
	s_mov_b64 s[6:7], 0x4b03400
	global_load_dwordx4 v[26:29], v[12:13], off offset:64
	global_load_dwordx4 v[30:33], v[12:13], off offset:128
	v_lshl_add_u64 v[18:19], v[10:11], 0, s[6:7]
	global_load_dwordx4 v[14:17], v[18:19], off offset:64
	global_load_dwordx4 v[34:37], v[12:13], off offset:192
	s_nop 0
	global_load_dwordx4 v[10:13], v[18:19], off offset:192
	s_lshl_b32 s3, s13, 7
	global_load_dwordx4 v[18:21], v[18:19], off offset:128
	v_lshlrev_b32_e32 v22, 3, v1
	v_or_b32_e32 v55, s5, v24
	v_lshlrev_b32_e32 v68, 2, v1
	s_cmp_eq_u32 s4, 0
	v_lshlrev_b32_e32 v22, 1, v22
	s_waitcnt vmcnt(6)
	v_mfma_f32_16x16x32_bf16 v[2:5], v[2:5], v[6:9], 0
	s_waitcnt vmcnt(3)
	v_mfma_f32_16x16x32_bf16 v[2:5], v[26:29], v[14:17], v[2:5]
	s_waitcnt vmcnt(0)
	v_mfma_f32_16x16x32_bf16 v[2:5], v[30:33], v[18:21], v[2:5]
	v_mfma_f32_16x16x32_bf16 v[2:5], v[34:37], v[10:13], v[2:5]
	s_cbranch_scc1 .LBB0_1785
	v_or_b32_e32 v23, 16, v25
	v_mov_b64_e32 v[26:27], s[92:93]
	v_mad_u64_u32 v[26:27], s[6:7], v23, s17, v[26:27]
	s_lshl_b32 s6, s3, 1
	s_mov_b32 s7, s84
	v_lshl_add_u64 v[26:27], v[26:27], 0, s[6:7]
	v_mov_b32_e32 v23, v0
	v_lshl_add_u64 v[30:31], v[26:27], 0, v[22:23]
	v_add_co_u32_e32 v26, vcc, 0x4b03000, v30
	v_lshl_add_u64 v[38:39], v[30:31], 0, s[18:19]
	s_nop 0
	v_addc_co_u32_e32 v27, vcc, 0, v31, vcc
	global_load_dwordx4 v[26:29], v[26:27], off offset:2048
	s_nop 0
	global_load_dwordx4 v[30:33], v[38:39], off offset:64
	global_load_dwordx4 v[34:37], v[38:39], off offset:192
	v_or_b32_e32 v23, 16, v68
	global_load_dwordx4 v[38:41], v[38:39], off offset:128
	v_cmp_gt_u32_e32 vcc, v23, v55
	s_waitcnt vmcnt(3)
	v_mfma_f32_16x16x32_bf16 v[26:29], v[26:29], v[6:9], 0
	s_waitcnt vmcnt(2)
	v_mfma_f32_16x16x32_bf16 v[26:29], v[30:33], v[14:17], v[26:29]
	v_mov_b32_e32 v30, s84
	v_or_b32_e32 v31, 17, v68
	v_or_b32_e32 v32, 18, v68
	s_waitcnt vmcnt(0)
	v_mfma_f32_16x16x32_bf16 v[26:29], v[38:41], v[18:21], v[26:29]
	v_or_b32_e32 v33, 19, v68
	v_mfma_f32_16x16x32_bf16 v[26:29], v[34:37], v[10:13], v[26:29]
	s_nop 7
	v_cndmask_b32_e32 v26, v26, v30, vcc
	v_cmp_le_u32_e32 vcc, v31, v55
	s_nop 1
	v_cndmask_b32_e32 v27, 0, v27, vcc
	v_cmp_le_u32_e32 vcc, v32, v55
	s_nop 1
	v_cndmask_b32_e32 v28, 0, v28, vcc
	v_cmp_le_u32_e32 vcc, v33, v55
	s_nop 1
	v_cndmask_b32_e32 v29, 0, v29, vcc
	s_branch .LBB0_1786

.LBB0_1790:
	s_ashr_i32 s3, s1, 1
	s_and_b32 s3, s3, 0xffffff80
	s_mov_b32 s9, s84
	v_or_b32_e32 v60, s3, v24
	s_lshl_b64 s[6:7], s[8:9], 10
	v_readlane_b32 s4, v255, 13
	s_or_b32 s6, s6, s2
	v_lshlrev_b32_e32 v24, 1, v68
	v_mov_b32_e32 v25, v0
	v_readlane_b32 s5, v255, 14
	v_ashrrev_i32_e32 v61, 31, v60
	v_mov_b32_e32 v42, s84
	v_lshl_add_u64 v[62:63], s[4:5], 0, v[24:25]
	v_lshl_add_u64 v[24:25], s[6:7], 0, v[60:61]
	v_lshlrev_b64 v[24:25], 7, v[24:25]
	v_lshl_add_u64 v[24:25], v[62:63], 0, v[24:25]
	global_load_dwordx2 v[38:39], v[24:25], off
	global_load_dwordx2 v[40:41], v[24:25], off offset:32
	v_cmp_gt_u32_e32 vcc, v68, v55
	v_cvt_pk_bf16_f32 v52, v26, v27
	v_cvt_pk_bf16_f32 v53, v28, v29
	v_cndmask_b32_e32 v37, v2, v42, vcc
	v_cmp_lt_u32_e32 vcc, v68, v55
	v_cvt_pk_bf16_f32 v46, v31, v32
	v_cvt_pk_bf16_f32 v47, v33, v34
	v_cndmask_b32_e32 v2, v37, v2, vcc
	v_or_b32_e32 v37, 2, v68
	v_cndmask_b32_e32 v3, 0, v3, vcc
	v_cmp_le_u32_e32 vcc, v37, v55
	v_or_b32_e32 v37, 3, v68
	v_cvt_pk_bf16_f32 v50, v2, v3
	v_cndmask_b32_e32 v4, 0, v4, vcc
	v_cmp_le_u32_e32 vcc, v37, v55
	v_cndmask_b32_e64 v2, 0, 1, s[10:11]
	v_cmp_ne_u32_e64 s[4:5], 1, v2
	v_cndmask_b32_e32 v5, 0, v5, vcc
	v_cvt_pk_bf16_f32 v51, v4, v5
	v_cvt_pk_bf16_f32 v48, v30, v23
	v_cvt_pk_bf16_f32 v49, v35, v36
	s_andn2_b64 vcc, exec, s[10:11]
	s_waitcnt vmcnt(0)
	v_mfma_f32_16x16x32_bf16 v[2:5], v[38:41], v[50:53], 0
	s_cbranch_vccnz .LBB0_1792
	global_load_dwordx2 v[26:27], v[24:25], off offset:64
	global_load_dwordx2 v[28:29], v[24:25], off offset:96
	s_waitcnt vmcnt(0)
	v_mfma_f32_16x16x32_bf16 v[2:5], v[26:29], v[46:49], v[2:5]
.LBB0_1792:
	s_lshl_b32 s9, s13, 6
	s_and_b32 s10, s12, 0xffffff00
	s_and_b32 s8, s8, 63
	s_or_b32 s9, s10, s9
	s_or_b32 s8, s9, s8
	s_mov_b32 s9, s84
	s_lshl_b64 s[8:9], s[8:9], 16
	v_readlane_b32 s10, v255, 15
	s_add_u32 s8, s10, s8
	v_readlane_b32 s10, v255, 16
	s_addc_u32 s9, s10, s9
	v_mov_b32_e32 v23, v0
	v_lshl_add_u64 v[58:59], s[8:9], 0, v[22:23]
	v_lshlrev_b64 v[22:23], 8, v[60:61]
	v_lshl_add_u64 v[34:35], v[58:59], 0, v[22:23]
	global_load_dwordx4 v[22:25], v[34:35], off
	global_load_dwordx4 v[26:29], v[34:35], off offset:64
	global_load_dwordx4 v[30:33], v[34:35], off offset:128
	s_and_b64 vcc, exec, s[4:5]
	s_waitcnt vmcnt(2)
	v_mfma_f32_16x16x32_bf16 v[2:5], v[22:25], v[6:9], v[2:5]
	v_or_b32_e32 v22, 16, v60
	v_ashrrev_i32_e32 v23, 31, v22
	v_lshl_add_u64 v[24:25], s[6:7], 0, v[22:23]
	s_waitcnt vmcnt(1)
	v_mfma_f32_16x16x32_bf16 v[2:5], v[26:29], v[14:17], v[2:5]
	global_load_dwordx4 v[26:29], v[34:35], off offset:192
	v_lshlrev_b64 v[24:25], 7, v[24:25]
	v_lshl_add_u64 v[24:25], v[62:63], 0, v[24:25]
	s_waitcnt vmcnt(1)
	v_mfma_f32_16x16x32_bf16 v[2:5], v[30:33], v[18:21], v[2:5]
	s_waitcnt vmcnt(0)
	v_mfma_f32_16x16x32_bf16 v[42:45], v[26:29], v[10:13], v[2:5]
	s_nop 5
	global_load_dwordx2 v[2:3], v[24:25], off
	global_load_dwordx2 v[4:5], v[24:25], off offset:32
	s_waitcnt vmcnt(0)
	v_mfma_f32_16x16x32_bf16 v[2:5], v[2:5], v[50:53], 0
	s_cbranch_vccnz .LBB0_1794
	global_load_dwordx2 v[26:27], v[24:25], off offset:64
	global_load_dwordx2 v[28:29], v[24:25], off offset:96
	s_waitcnt vmcnt(0)
	v_mfma_f32_16x16x32_bf16 v[2:5], v[26:29], v[46:49], v[2:5]
.LBB0_1794:
	v_lshlrev_b64 v[22:23], 8, v[22:23]
	v_lshl_add_u64 v[34:35], v[58:59], 0, v[22:23]
	global_load_dwordx4 v[22:25], v[34:35], off
	global_load_dwordx4 v[26:29], v[34:35], off offset:64
	global_load_dwordx4 v[30:33], v[34:35], off offset:128
	s_and_b64 vcc, exec, s[4:5]
	s_waitcnt vmcnt(2)
	v_mfma_f32_16x16x32_bf16 v[2:5], v[22:25], v[6:9], v[2:5]
	v_or_b32_e32 v22, 32, v60
	v_ashrrev_i32_e32 v23, 31, v22
	v_lshl_add_u64 v[24:25], s[6:7], 0, v[22:23]
	s_waitcnt vmcnt(1)
	v_mfma_f32_16x16x32_bf16 v[2:5], v[26:29], v[14:17], v[2:5]
	global_load_dwordx4 v[26:29], v[34:35], off offset:192
	v_lshlrev_b64 v[24:25], 7, v[24:25]
	v_lshl_add_u64 v[24:25], v[62:63], 0, v[24:25]
	s_waitcnt vmcnt(1)
	v_mfma_f32_16x16x32_bf16 v[2:5], v[30:33], v[18:21], v[2:5]
	s_waitcnt vmcnt(0)
	v_mfma_f32_16x16x32_bf16 v[38:41], v[26:29], v[10:13], v[2:5]
	s_nop 5
	global_load_dwordx2 v[2:3], v[24:25], off
	global_load_dwordx2 v[4:5], v[24:25], off offset:32
	s_waitcnt vmcnt(0)
	v_mfma_f32_16x16x32_bf16 v[2:5], v[2:5], v[50:53], 0
	s_cbranch_vccnz .LBB0_1796
	global_load_dwordx2 v[26:27], v[24:25], off offset:64
	global_load_dwordx2 v[28:29], v[24:25], off offset:96
	s_waitcnt vmcnt(0)
	v_mfma_f32_16x16x32_bf16 v[2:5], v[26:29], v[46:49], v[2:5]
.LBB0_1796:
	v_lshlrev_b64 v[22:23], 8, v[22:23]
	v_lshl_add_u64 v[34:35], v[58:59], 0, v[22:23]
	global_load_dwordx4 v[22:25], v[34:35], off
	global_load_dwordx4 v[26:29], v[34:35], off offset:64
	global_load_dwordx4 v[30:33], v[34:35], off offset:128
	s_and_b64 vcc, exec, s[4:5]
	s_waitcnt vmcnt(2)
	v_mfma_f32_16x16x32_bf16 v[2:5], v[22:25], v[6:9], v[2:5]
	v_or_b32_e32 v22, 48, v60
	v_ashrrev_i32_e32 v23, 31, v22
	v_lshl_add_u64 v[24:25], s[6:7], 0, v[22:23]
	s_waitcnt vmcnt(1)
	v_mfma_f32_16x16x32_bf16 v[2:5], v[26:29], v[14:17], v[2:5]
	global_load_dwordx4 v[26:29], v[34:35], off offset:192
	v_lshlrev_b64 v[24:25], 7, v[24:25]
	v_lshl_add_u64 v[24:25], v[62:63], 0, v[24:25]
	s_waitcnt vmcnt(1)
	v_mfma_f32_16x16x32_bf16 v[2:5], v[30:33], v[18:21], v[2:5]
	s_waitcnt vmcnt(0)
	v_mfma_f32_16x16x32_bf16 v[34:37], v[26:29], v[10:13], v[2:5]
	s_nop 5
	global_load_dwordx2 v[2:3], v[24:25], off
	global_load_dwordx2 v[4:5], v[24:25], off offset:32
	s_waitcnt vmcnt(0)
	v_mfma_f32_16x16x32_bf16 v[2:5], v[2:5], v[50:53], 0
	s_cbranch_vccnz .LBB0_1798
	global_load_dwordx2 v[26:27], v[24:25], off offset:64
	global_load_dwordx2 v[28:29], v[24:25], off offset:96
	s_waitcnt vmcnt(0)
	v_mfma_f32_16x16x32_bf16 v[2:5], v[26:29], v[46:49], v[2:5]
.LBB0_1798:
	v_lshlrev_b64 v[22:23], 8, v[22:23]
	v_lshl_add_u64 v[64:65], v[58:59], 0, v[22:23]
	global_load_dwordx4 v[22:25], v[64:65], off
	global_load_dwordx4 v[26:29], v[64:65], off offset:64
	global_load_dwordx4 v[30:33], v[64:65], off offset:128
	s_and_b64 vcc, exec, s[4:5]
	s_waitcnt vmcnt(2)
	v_mfma_f32_16x16x32_bf16 v[2:5], v[22:25], v[6:9], v[2:5]
	v_or_b32_e32 v22, 64, v60
	v_ashrrev_i32_e32 v23, 31, v22
	v_lshl_add_u64 v[24:25], s[6:7], 0, v[22:23]
	s_waitcnt vmcnt(1)
	v_mfma_f32_16x16x32_bf16 v[2:5], v[26:29], v[14:17], v[2:5]
	global_load_dwordx4 v[26:29], v[64:65], off offset:192
	v_lshlrev_b64 v[24:25], 7, v[24:25]
	v_lshl_add_u64 v[24:25], v[62:63], 0, v[24:25]
	s_waitcnt vmcnt(1)
	v_mfma_f32_16x16x32_bf16 v[2:5], v[30:33], v[18:21], v[2:5]
	s_waitcnt vmcnt(0)
	v_mfma_f32_16x16x32_bf16 v[30:33], v[26:29], v[10:13], v[2:5]
	s_nop 5
	global_load_dwordx2 v[2:3], v[24:25], off
	global_load_dwordx2 v[4:5], v[24:25], off offset:32
	s_waitcnt vmcnt(0)
	v_mfma_f32_16x16x32_bf16 v[2:5], v[2:5], v[50:53], 0
	s_cbranch_vccnz .LBB0_1800
	global_load_dwordx2 v[26:27], v[24:25], off offset:64
	global_load_dwordx2 v[28:29], v[24:25], off offset:96
	s_waitcnt vmcnt(0)
	v_mfma_f32_16x16x32_bf16 v[2:5], v[26:29], v[46:49], v[2:5]
.LBB0_1800:
	v_lshlrev_b64 v[22:23], 8, v[22:23]
	v_lshl_add_u64 v[70:71], v[58:59], 0, v[22:23]
	global_load_dwordx4 v[22:25], v[70:71], off
	global_load_dwordx4 v[26:29], v[70:71], off offset:64
	global_load_dwordx4 v[64:67], v[70:71], off offset:128
	s_and_b64 vcc, exec, s[4:5]
	s_waitcnt vmcnt(2)
	v_mfma_f32_16x16x32_bf16 v[2:5], v[22:25], v[6:9], v[2:5]
	v_or_b32_e32 v22, 0x50, v60
	v_ashrrev_i32_e32 v23, 31, v22
	v_lshl_add_u64 v[24:25], s[6:7], 0, v[22:23]
	s_waitcnt vmcnt(1)
	v_mfma_f32_16x16x32_bf16 v[2:5], v[26:29], v[14:17], v[2:5]
	global_load_dwordx4 v[26:29], v[70:71], off offset:192
	v_lshlrev_b64 v[24:25], 7, v[24:25]
	v_lshl_add_u64 v[24:25], v[62:63], 0, v[24:25]
	s_waitcnt vmcnt(1)
	v_mfma_f32_16x16x32_bf16 v[2:5], v[64:67], v[18:21], v[2:5]
	s_waitcnt vmcnt(0)
	v_mfma_f32_16x16x32_bf16 v[26:29], v[26:29], v[10:13], v[2:5]
	s_nop 5
	global_load_dwordx2 v[2:3], v[24:25], off
	global_load_dwordx2 v[4:5], v[24:25], off offset:32
	s_waitcnt vmcnt(0)
	v_mfma_f32_16x16x32_bf16 v[2:5], v[2:5], v[50:53], 0
	s_cbranch_vccnz .LBB0_1802
	global_load_dwordx2 v[64:65], v[24:25], off offset:64
	global_load_dwordx2 v[66:67], v[24:25], off offset:96
	s_waitcnt vmcnt(0)
	v_mfma_f32_16x16x32_bf16 v[2:5], v[64:67], v[46:49], v[2:5]
.LBB0_1802:
	v_lshlrev_b64 v[22:23], 8, v[22:23]
	v_lshl_add_u64 v[70:71], v[58:59], 0, v[22:23]
	global_load_dwordx4 v[22:25], v[70:71], off
	global_load_dwordx4 v[64:67], v[70:71], off offset:64
	s_and_b64 vcc, exec, s[4:5]
	s_waitcnt vmcnt(1)
	v_mfma_f32_16x16x32_bf16 v[2:5], v[22:25], v[6:9], v[2:5]
	global_load_dwordx4 v[22:25], v[70:71], off offset:128
	s_nop 0
	global_load_dwordx4 v[70:73], v[70:71], off offset:192
	s_waitcnt vmcnt(2)
	v_mfma_f32_16x16x32_bf16 v[2:5], v[64:67], v[14:17], v[2:5]
	v_or_b32_e32 v64, 0x60, v60
	v_ashrrev_i32_e32 v65, 31, v64
	s_waitcnt vmcnt(1)
	v_mfma_f32_16x16x32_bf16 v[2:5], v[22:25], v[18:21], v[2:5]
	v_lshl_add_u64 v[22:23], s[6:7], 0, v[64:65]
	v_lshlrev_b64 v[22:23], 7, v[22:23]
	v_lshl_add_u64 v[66:67], v[62:63], 0, v[22:23]
	s_waitcnt vmcnt(0)
	v_mfma_f32_16x16x32_bf16 v[22:25], v[70:73], v[10:13], v[2:5]
	s_nop 2
	global_load_dwordx2 v[2:3], v[66:67], off
	global_load_dwordx2 v[4:5], v[66:67], off offset:32
	s_waitcnt vmcnt(0)
	v_mfma_f32_16x16x32_bf16 v[2:5], v[2:5], v[50:53], 0
	s_cbranch_vccnz .LBB0_1804
	global_load_dwordx2 v[70:71], v[66:67], off offset:64
	global_load_dwordx2 v[72:73], v[66:67], off offset:96
	s_waitcnt vmcnt(0)
	v_mfma_f32_16x16x32_bf16 v[2:5], v[70:73], v[46:49], v[2:5]
.LBB0_1804:
	v_lshlrev_b64 v[64:65], 8, v[64:65]
	v_lshl_add_u64 v[74:75], v[58:59], 0, v[64:65]
	global_load_dwordx4 v[64:67], v[74:75], off
	global_load_dwordx4 v[70:73], v[74:75], off offset:64
	v_or_b32_e32 v60, 0x70, v60
	v_ashrrev_i32_e32 v61, 31, v60
	s_and_b64 vcc, exec, s[4:5]
	s_waitcnt vmcnt(1)
	v_mfma_f32_16x16x32_bf16 v[2:5], v[64:67], v[6:9], v[2:5]
	global_load_dwordx4 v[64:67], v[74:75], off offset:128
	s_waitcnt vmcnt(1)
	v_mfma_f32_16x16x32_bf16 v[2:5], v[70:73], v[14:17], v[2:5]
	global_load_dwordx4 v[70:73], v[74:75], off offset:192
	s_waitcnt vmcnt(1)
	v_mfma_f32_16x16x32_bf16 v[2:5], v[64:67], v[18:21], v[2:5]
	v_lshl_add_u64 v[64:65], s[6:7], 0, v[60:61]
	v_lshlrev_b64 v[64:65], 7, v[64:65]
	v_lshl_add_u64 v[62:63], v[62:63], 0, v[64:65]
	global_load_dwordx2 v[64:65], v[62:63], off
	global_load_dwordx2 v[66:67], v[62:63], off offset:32
	s_waitcnt vmcnt(2)
	v_mfma_f32_16x16x32_bf16 v[2:5], v[70:73], v[10:13], v[2:5]
	s_waitcnt vmcnt(0)
	v_mfma_f32_16x16x32_bf16 v[50:53], v[64:67], v[50:53], 0
	s_cbranch_vccnz .LBB0_1806
	global_load_dwordx2 v[64:65], v[62:63], off offset:64
	global_load_dwordx2 v[66:67], v[62:63], off offset:96
	s_waitcnt vmcnt(0)
	v_mfma_f32_16x16x32_bf16 v[50:53], v[64:67], v[46:49], v[50:53]
